# raise wave priority (s_setprio 2) only around the three chained score MFMAs of each sample-attn K-pass tail, so the younger wave's chain is not starved by its partner's MFMA burst
# speedup vs baseline: 1.0142x; 1.0142x over previous
.LBB0_1867:
	v_add_u32_e32 v204, 0, v216
	v_add_u32_e32 v154, 0x12080, v204
	v_add_u32_e32 v196, 0x120c0, v204
	ds_read_b128 v[154:157], v154
	ds_read_b128 v[196:199], v196
	v_and_or_b32 v200, s50, 48, v183
	v_mad_u32_u24 v205, v200, s77, v185
	v_add_u32_e32 v237, 0x12100, v204
	v_mfma_f32_16x16x32_bf16 v[200:203], v[2:5], v[146:149], 0
	ds_read_b128 v[238:241], v237
	v_mfma_f32_16x16x32_bf16 v[220:223], v[6:9], v[146:149], 0
	v_mfma_f32_16x16x32_bf16 v[224:227], v[10:13], v[146:149], 0
	v_mfma_f32_16x16x32_bf16 v[146:149], v[14:17], v[146:149], 0
	v_mfma_f32_16x16x32_bf16 v[200:203], v[18:21], v[150:153], v[200:203]
	v_mfma_f32_16x16x32_bf16 v[220:223], v[22:25], v[150:153], v[220:223]
	v_mfma_f32_16x16x32_bf16 v[224:227], v[26:29], v[150:153], v[224:227]
	v_mfma_f32_16x16x32_bf16 v[146:149], v[30:33], v[150:153], v[146:149]
	v_add_u32_e32 v150, 0x12140, v204
	ds_read_b128 v[150:153], v150
	s_waitcnt lgkmcnt(2)
	v_mfma_f32_16x16x32_bf16 v[200:203], v[34:37], v[154:157], v[200:203]
	v_mfma_f32_16x16x32_bf16 v[220:223], v[38:41], v[154:157], v[220:223]
	v_mfma_f32_16x16x32_bf16 v[224:227], v[42:45], v[154:157], v[224:227]
	v_mfma_f32_16x16x32_bf16 v[146:149], v[46:49], v[154:157], v[146:149]
	v_add_u32_e32 v154, 0x12180, v204
	ds_read_b128 v[154:157], v154
	v_mfma_f32_16x16x32_bf16 v[200:203], v[50:53], v[196:199], v[200:203]
	v_mfma_f32_16x16x32_bf16 v[220:223], v[54:57], v[196:199], v[220:223]
	v_mfma_f32_16x16x32_bf16 v[224:227], v[58:61], v[196:199], v[224:227]
	v_mfma_f32_16x16x32_bf16 v[146:149], v[62:65], v[196:199], v[146:149]
	v_add_u32_e32 v196, 0x121c0, v204
	ds_read_b128 v[196:199], v196
	s_waitcnt lgkmcnt(3)
	v_mfma_f32_16x16x32_bf16 v[200:203], v[66:69], v[238:241], v[200:203]
	v_mfma_f32_16x16x32_bf16 v[220:223], v[70:73], v[238:241], v[220:223]
	v_mfma_f32_16x16x32_bf16 v[224:227], v[74:77], v[238:241], v[224:227]
	v_mfma_f32_16x16x32_bf16 v[238:241], v[78:81], v[238:241], v[146:149]
	s_nop 2
	ds_read_b128 v[146:149], v205
	s_waitcnt lgkmcnt(3)
	v_mfma_f32_16x16x32_bf16 v[200:203], v[82:85], v[150:153], v[200:203]
	v_mfma_f32_16x16x32_bf16 v[220:223], v[86:89], v[150:153], v[220:223]
	v_mfma_f32_16x16x32_bf16 v[224:227], v[90:93], v[150:153], v[224:227]
	v_mfma_f32_16x16x32_bf16 v[238:241], v[94:97], v[150:153], v[238:241]
	ds_read_b128 v[150:153], v205 offset:64
	s_waitcnt lgkmcnt(3)
	v_mfma_f32_16x16x32_bf16 v[200:203], v[98:101], v[154:157], v[200:203]
	v_mfma_f32_16x16x32_bf16 v[220:223], v[102:105], v[154:157], v[220:223]
	v_mfma_f32_16x16x32_bf16 v[224:227], v[106:109], v[154:157], v[224:227]
	v_mfma_f32_16x16x32_bf16 v[154:157], v[110:113], v[154:157], v[238:241]
	s_waitcnt lgkmcnt(2)
	v_mfma_f32_16x16x32_bf16 v[220:223], v[118:121], v[196:199], v[220:223]
	v_mfma_f32_16x16x32_bf16 v[154:157], v[126:129], v[196:199], v[154:157]
	v_mfma_f32_16x16x32_bf16 v[200:203], v[114:117], v[196:199], v[200:203]
	v_mfma_f32_16x16x32_bf16 v[224:227], v[122:125], v[196:199], v[224:227]
	ds_read_b128 v[196:199], v217
	ds_read_b128 v[242:245], v214 offset:128
	ds_read_b32 v255, v218
	s_nop 4
	v_mul_f32_e32 v204, v201, v201
	v_mul_f32_e32 v205, v203, v203
	v_fmac_f32_e32 v204, v200, v200
	v_fmac_f32_e32 v205, v202, v202
	v_add_f32_e32 v204, v204, v205
	v_mul_f32_e32 v205, v221, v221
	v_mul_f32_e32 v237, v223, v223
	v_fmac_f32_e32 v205, v220, v220
	v_fmac_f32_e32 v237, v222, v222
	v_add_f32_e32 v205, v205, v237
	v_add_f32_e32 v204, v204, v205
	v_mul_f32_e32 v205, v225, v225
	v_mul_f32_e32 v237, v227, v227
	v_fmac_f32_e32 v205, v224, v224
	v_fmac_f32_e32 v237, v226, v226
	v_add_f32_e32 v205, v205, v237
	v_add_f32_e32 v204, v204, v205
	v_mul_f32_e32 v205, v155, v155
	v_mul_f32_e32 v237, v157, v157
	v_fmac_f32_e32 v205, v154, v154
	v_fmac_f32_e32 v237, v156, v156
	v_add_f32_e32 v205, v205, v237
	v_add_f32_e32 v204, v204, v205
	v_mov_b32_e32 v205, v204
	v_cvt_pk_bf16_f32 v200, v200, v201
	v_cvt_pk_bf16_f32 v201, v202, v203
	v_permlane16_swap_b32_e32 v204, v205
	v_cvt_pk_bf16_f32 v202, v220, v221
	v_cvt_pk_bf16_f32 v203, v222, v223
	v_add_f32_e32 v204, v204, v205
	v_mov_b32_e32 v205, v204
	v_cvt_pk_bf16_f32 v220, v224, v225
	v_cvt_pk_bf16_f32 v221, v226, v227
	v_permlane32_swap_b32_e32 v204, v205
	v_cvt_pk_bf16_f32 v222, v154, v155
	v_cvt_pk_bf16_f32 v223, v156, v157
	v_add_f32_e32 v204, v204, v205
	s_waitcnt lgkmcnt(0)
	v_cndmask_b32_e64 v242, 0, v242, s[4:5]
	v_cndmask_b32_e64 v243, 0, v243, s[4:5]
	s_setprio 2
	v_mfma_f32_16x16x32_bf16 v[238:241], v[174:177], v[200:203], 0
	v_cndmask_b32_e64 v244, 0, v244, s[4:5]
	v_cndmask_b32_e64 v245, 0, v245, s[4:5]
	v_mfma_f32_16x16x32_bf16 v[238:241], v[246:249], v[220:223], v[238:241]
	v_add_f32_e32 v255, v204, v255
	v_fmamk_f32 v255, v255, 0x3c2aaaab, v231
	v_mfma_f32_16x16x32_bf16 v[238:241], v[242:245], v[196:199], v[238:241]
	s_setprio 0
	v_rsq_f32_e32 v255, v255
	s_add_i32 s50, s50, 16
	v_add_u32_e32 v218, 64, v218
	v_add_u32_e32 v217, 0x500, v217
	v_add_u32_e32 v216, 0x2100, v216
	v_mov_b32_e32 v178, v179
	v_mov_b32_e32 v179, v180
	v_mov_b32_e32 v180, v219
	v_mul_f32_e32 v200, v238, v255
	v_mul_f32_e32 v201, v239, v255
	v_mul_f32_e32 v202, v240, v255
	v_mul_f32_e32 v203, v241, v255
	s_nop 0
	v_permlane16_swap_b32_e32 v200, v201
	s_nop 0
	v_permlane16_swap_b32_e32 v202, v203
	s_nop 1
	v_permlane32_swap_b32_e32 v200, v202
	v_mov_b32_e32 v219, v200
	s_cmpk_lg_i32 s50, 48
	s_cbranch_scc1 .Lsa_nodma
	s_ashr_i32 s89, s46, 31
	s_mov_b32 s88, s46
	s_lshl_b64 s[88:89], s[88:89], 7
	s_lshl_b32 s90, s80, 6
	s_and_b32 s90, s90, 64
	s_or_b32 s88, s88, s90
	s_lshl_b64 s[90:91], s[88:89], 10
	s_lshl_b64 s[88:89], s[88:89], 7
	v_lshl_add_u64 v[204:205], v[158:159], 0, s[90:91]
	v_lshl_add_u64 v[200:201], v[204:205], 0, s[20:21]
	s_mov_b32 m0, s54
	s_nop 0
	global_load_lds_dwordx4 v[200:201], off
	v_lshl_add_u64 v[200:201], v[204:205], 0, s[30:31]
	s_mov_b32 m0, s55
	s_nop 0
	global_load_lds_dwordx4 v[200:201], off
	v_lshl_add_u64 v[200:201], v[204:205], 0, s[34:35]
	s_mov_b32 m0, s56
	s_nop 0
	global_load_lds_dwordx4 v[200:201], off
	v_lshl_add_u64 v[200:201], v[204:205], 0, s[36:37]
	s_mov_b32 m0, s57
	s_nop 0
	global_load_lds_dwordx4 v[200:201], off
	v_lshl_add_u64 v[200:201], v[204:205], 0, s[38:39]
	s_mov_b32 m0, s58
	s_nop 0
	global_load_lds_dwordx4 v[200:201], off
	v_lshl_add_u64 v[200:201], v[204:205], 0, s[40:41]
	s_mov_b32 m0, s59
	s_nop 0
	global_load_lds_dwordx4 v[200:201], off
	v_lshl_add_u64 v[200:201], v[204:205], 0, s[42:43]
	s_mov_b32 m0, s60
	s_nop 0
	global_load_lds_dwordx4 v[200:201], off
	v_lshl_add_u64 v[200:201], v[204:205], 0, s[44:45]
	s_mov_b32 m0, s61
	s_nop 0
	global_load_lds_dwordx4 v[200:201], off
	v_lshl_add_u64 v[200:201], v[160:161], 0, s[88:89]
	s_mov_b32 m0, s28
	s_nop 0
	global_load_lds_dwordx4 v[200:201], off
